# HGRN chunk: gate/decay stages parallelised, state-update KET/V reads prefetched with counted waits
# speedup vs baseline: 1.0041x; 1.0041x over previous
; #define LAS __attribute__((address_space(3)))
; __device__ __forceinline__ f32x4 mfma16(bf16x8 a, bf16x8 b, f32x4 c) { return __builtin_amdgcn_mfma_f32_16x16x32_bf16(a, b, c, 0, 0, 0); }
; __device__ __forceinline__ s16x4 ldtr(const LAS unsigned char* p) { return __builtin_bit_cast(s16x4, __builtin_amdgcn_ds_read_tr16_b64_v4i16((LAS v4i16_t*)p)); }
; __device__ __forceinline__ void hgrn_unit(LAS unsigned char* lds, bf16_t* zC, int bl, int h, int dir, float lb, int tid, bf16_t* ob, int ostr, int ocol) {
;     ...
;         f32x4 o[4];
; #pragma unroll
;         for (int tt = 0; tt < 4; ++tt) o[tt] = (f32x4){0.f, 0.f, 0.f, 0.f};
; #pragma unroll
;         for (int sb = 0; sb < 2; ++sb) {
;             f32x4 at[2][4];
; #pragma unroll
;             for (int ts = 0; ts < 2; ++ts)
; #pragma unroll
;                 for (int tt = 0; tt < 4; ++tt) at[ts][tt] = (f32x4){0.f, 0.f, 0.f, 0.f};
; #pragma unroll
;             for (int ks = 0; ks < 4; ++ks) {
;                 bf16x8 qf[4];
; #pragma unroll
;                 for (int tt = 0; tt < 4; ++tt) if (tt >= 2 * sb) qf[tt] = *(const LAS bf16x8*)(lds + HG_QE + (tt * 16 + fr) * 272 + (ks * 32 + quad * 8) * 2);
;                 if (sb == 0) {
;                     const bf16x8 sa = *(const LAS bf16x8*)(lds + HG_STB + (wv * 16 + fr) * 272 + (ks * 32 + quad * 8) * 2);
; #pragma unroll
;                     for (int tt = 0; tt < 4; ++tt) o[tt] = mfma16(sa, qf[tt], o[tt]);
;                 }
; #pragma unroll
;                 for (int ts = 0; ts < 2; ++ts) {
;                     const int a = sb * 2 + ts;
;                     const bf16x8 kf = *(const LAS bf16x8*)(lds + HG_KN + (a * 16 + fr) * 272 + (ks * 32 + quad * 8) * 2);
; #pragma unroll
;                     for (int tt = 0; tt < 4; ++tt) if (tt >= a) at[ts][tt] = mfma16(kf, qf[tt], at[ts][tt]);
;                 }
;             }
; #pragma unroll
;             for (int ts = 0; ts < 2; ++ts)
; #pragma unroll
;                 for (int j = 0; j < 4; ++j) at[ts][sb * 2 + ts][j] = (quad * 4 + j > fr) ? 0.f : at[ts][sb * 2 + ts][j];
;             const LAS unsigned char* vp = lds + HG_VV + (sb * 32 + quad * 4 + (fr >> 2)) * 288 + (wv * 16 + (fr & 3) * 4) * 2;
;             const bf16x8 vf = cat8(ldtr(vp), ldtr(vp + 16 * 288));
; #pragma unroll
;             for (int tt = 0; tt < 4; ++tt) if (tt >= 2 * sb) o[tt] = mfma16(vf, pack8(at[0][tt], at[1][tt]), o[tt]);
;         }
.LBB0_193:
	ds_read_b128 v[60:63], v112
	ds_read_b128 v[64:67], v112 offset:4352
	ds_read_b128 v[72:75], v112 offset:8704
	ds_read_b128 v[68:71], v112 offset:13056
	ds_read_b128 v[76:79], v113
	ds_read_b128 v[126:129], v112 offset:17408
	ds_read_b128 v[144:147], v112 offset:21760
	ds_read_b128 v[156:159], v112 offset:64
	ds_read_b128 v[160:163], v112 offset:4416
	ds_read_b128 v[164:167], v112 offset:8768
	ds_read_b128 v[168:171], v112 offset:13120
	ds_read_b128 v[188:191], v113 offset:64
	v_subrev_u32_e32 v102, 64, v102
	s_waitcnt lgkmcnt(7)
	v_mfma_f32_16x16x32_bf16 v[80:83], v[76:79], v[60:63], 0
	v_subrev_u32_e32 v104, 64, v104
	v_mfma_f32_16x16x32_bf16 v[118:121], v[76:79], v[64:67], 0
	v_mfma_f32_16x16x32_bf16 v[122:125], v[76:79], v[72:75], 0
	v_mfma_f32_16x16x32_bf16 v[76:79], v[76:79], v[68:71], 0
	s_waitcnt lgkmcnt(0)
	v_mfma_f32_16x16x32_bf16 v[80:83], v[188:191], v[156:159], v[80:83]
	v_mfma_f32_16x16x32_bf16 v[118:121], v[188:191], v[160:163], v[118:121]
	v_mfma_f32_16x16x32_bf16 v[122:125], v[188:191], v[164:167], v[122:125]
	v_mfma_f32_16x16x32_bf16 v[76:79], v[188:191], v[168:171], v[76:79]
	ds_read_b128 v[188:191], v112 offset:17472
	v_mfma_f32_16x16x32_bf16 v[60:63], v[126:129], v[60:63], 0
	s_waitcnt lgkmcnt(0)
	v_mfma_f32_16x16x32_bf16 v[60:63], v[188:191], v[156:159], v[60:63]
	ds_read_b128 v[156:159], v112 offset:21824
	v_mfma_f32_16x16x32_bf16 v[130:133], v[126:129], v[64:67], 0
	v_mfma_f32_16x16x32_bf16 v[134:137], v[126:129], v[72:75], 0
	v_mfma_f32_16x16x32_bf16 v[126:129], v[126:129], v[68:71], 0
	v_mfma_f32_16x16x32_bf16 v[64:67], v[144:147], v[64:67], 0
	v_mfma_f32_16x16x32_bf16 v[152:155], v[144:147], v[72:75], 0
	v_mfma_f32_16x16x32_bf16 v[144:147], v[144:147], v[68:71], 0
	v_mfma_f32_16x16x32_bf16 v[130:133], v[188:191], v[160:163], v[130:133]
	v_mfma_f32_16x16x32_bf16 v[134:137], v[188:191], v[164:167], v[134:137]
	v_mfma_f32_16x16x32_bf16 v[126:129], v[188:191], v[168:171], v[126:129]
	s_waitcnt lgkmcnt(0)
	v_mfma_f32_16x16x32_bf16 v[64:67], v[156:159], v[160:163], v[64:67]
	v_mfma_f32_16x16x32_bf16 v[152:155], v[156:159], v[164:167], v[152:155]
	v_mfma_f32_16x16x32_bf16 v[144:147], v[156:159], v[168:171], v[144:147]
	ds_read_b128 v[156:159], v112 offset:128
	ds_read_b128 v[160:163], v112 offset:4480
	ds_read_b128 v[164:167], v112 offset:8832
	ds_read_b128 v[168:171], v112 offset:13184
	ds_read_b128 v[188:191], v113 offset:128
	s_waitcnt lgkmcnt(0)
	v_mfma_f32_16x16x32_bf16 v[80:83], v[188:191], v[156:159], v[80:83]
	v_mfma_f32_16x16x32_bf16 v[118:121], v[188:191], v[160:163], v[118:121]
	v_mfma_f32_16x16x32_bf16 v[122:125], v[188:191], v[164:167], v[122:125]
	v_mfma_f32_16x16x32_bf16 v[76:79], v[188:191], v[168:171], v[76:79]
	ds_read_b128 v[188:191], v112 offset:17536
	s_waitcnt lgkmcnt(0)
	v_mfma_f32_16x16x32_bf16 v[60:63], v[188:191], v[156:159], v[60:63]
	ds_read_b128 v[156:159], v112 offset:21888
	v_mfma_f32_16x16x32_bf16 v[130:133], v[188:191], v[160:163], v[130:133]
	v_mfma_f32_16x16x32_bf16 v[134:137], v[188:191], v[164:167], v[134:137]
	v_mfma_f32_16x16x32_bf16 v[126:129], v[188:191], v[168:171], v[126:129]
	s_waitcnt lgkmcnt(0)
	v_mfma_f32_16x16x32_bf16 v[64:67], v[156:159], v[160:163], v[64:67]
	v_mfma_f32_16x16x32_bf16 v[152:155], v[156:159], v[164:167], v[152:155]
	v_mfma_f32_16x16x32_bf16 v[144:147], v[156:159], v[168:171], v[144:147]
	ds_read_b128 v[156:159], v112 offset:192
	ds_read_b128 v[160:163], v112 offset:4544
	ds_read_b128 v[164:167], v112 offset:8896
	ds_read_b128 v[168:171], v112 offset:13248
	ds_read_b128 v[188:191], v113 offset:192
	s_waitcnt lgkmcnt(0)
	v_mfma_f32_16x16x32_bf16 v[80:83], v[188:191], v[156:159], v[80:83]
	v_mfma_f32_16x16x32_bf16 v[118:121], v[188:191], v[160:163], v[118:121]
	v_mfma_f32_16x16x32_bf16 v[122:125], v[188:191], v[164:167], v[122:125]
	v_mfma_f32_16x16x32_bf16 v[76:79], v[188:191], v[168:171], v[76:79]
	ds_read_b128 v[188:191], v112 offset:17600
	s_waitcnt lgkmcnt(0)
	v_mfma_f32_16x16x32_bf16 v[60:63], v[188:191], v[156:159], v[60:63]
	ds_read_b128 v[156:159], v112 offset:21952
	s_nop 6
	v_cndmask_b32_e64 v0, v60, 0, s[50:51]
	s_waitcnt lgkmcnt(0)
	v_mfma_f32_16x16x32_bf16 v[64:67], v[156:159], v[160:163], v[64:67]
	v_cndmask_b32_e64 v1, 0, v61, s[52:53]
	v_cndmask_b32_e64 v3, v62, 0, s[54:55]
	v_cndmask_b32_e64 v60, v63, 0, s[56:57]
	v_mfma_f32_16x16x32_bf16 v[130:133], v[188:191], v[160:163], v[130:133]
	s_nop 3
	v_cndmask_b32_e64 v138, v64, 0, s[50:51]
	v_cndmask_b32_e64 v139, 0, v65, s[52:53]
	v_cndmask_b32_e64 v140, v66, 0, s[54:55]
	v_mfma_f32_16x16x32_bf16 v[152:155], v[156:159], v[164:167], v[152:155]
	v_cndmask_b32_e64 v141, v67, 0, s[56:57]
	v_cvt_pk_bf16_f32 v0, v0, v1
	v_cvt_pk_bf16_f32 v1, v3, v60
	v_mfma_f32_16x16x32_bf16 v[144:147], v[156:159], v[168:171], v[144:147]
	ds_read_b64_tr_b16 v[156:157], v97 offset:53248
	ds_read_b64_tr_b16 v[158:159], v97 offset:57856
	v_mov_b32_e32 v3, v2
	v_cvt_pk_bf16_f32 v60, v130, v131
	v_mfma_f32_16x16x32_bf16 v[134:137], v[188:191], v[164:167], v[134:137]
	v_cvt_pk_bf16_f32 v61, v132, v133
	v_cvt_pk_bf16_f32 v62, v138, v139
	v_cvt_pk_bf16_f32 v63, v140, v141
	v_mfma_f32_16x16x32_bf16 v[126:129], v[188:191], v[168:171], v[126:129]
	s_waitcnt lgkmcnt(0)
	v_mfma_f32_16x16x32_bf16 v[64:67], v[156:159], v[0:3], v[80:83]
	v_mfma_f32_16x16x32_bf16 v[60:63], v[156:159], v[60:63], v[118:121]
	s_nop 1
	v_cvt_pk_bf16_f32 v80, v134, v135
	v_cvt_pk_bf16_f32 v81, v136, v137
	v_cvt_pk_bf16_f32 v82, v152, v153
	v_cvt_pk_bf16_f32 v83, v154, v155
	v_cvt_pk_bf16_f32 v118, v126, v127
	v_cvt_pk_bf16_f32 v119, v128, v129
	v_cvt_pk_bf16_f32 v120, v144, v145
	v_cvt_pk_bf16_f32 v121, v146, v147
	v_mfma_f32_16x16x32_bf16 v[80:83], v[156:159], v[80:83], v[122:125]
	s_nop 0
	v_mfma_f32_16x16x32_bf16 v[76:79], v[156:159], v[118:121], v[76:79]
	ds_read_b128 v[118:121], v114 offset:17408
	ds_read_b128 v[122:125], v114 offset:21760
	s_waitcnt lgkmcnt(1)
; #define LAS __attribute__((address_space(3)))
; __device__ __forceinline__ unsigned pk2(float lo, float hi) { f32x2 v = {lo, hi}; bf16x2_t b = __builtin_convertvector(v, bf16x2_t); return __builtin_bit_cast(unsigned, b); }
; __device__ __forceinline__ f32x4 mfma16(bf16x8 a, bf16x8 b, f32x4 c) { return __builtin_amdgcn_mfma_f32_16x16x32_bf16(a, b, c, 0, 0, 0); }
; __device__ __forceinline__ s16x4 ldtr(const LAS unsigned char* p) { return __builtin_bit_cast(s16x4, __builtin_amdgcn_ds_read_tr16_b64_v4i16((LAS v4i16_t*)p)); }
; __device__ __forceinline__ bf16x8 pack8(f32x4 a, f32x4 b) { u32x4 w; w.x = pk2(a[0], a[1]); w.y = pk2(a[2], a[3]); w.z = pk2(b[0], b[1]); w.w = pk2(b[2], b[3]); return __builtin_bit_cast(bf16x8, w); }
; __device__ __forceinline__ void hgrn_unit(LAS unsigned char* lds, bf16_t* zC, int bl, int h, int dir, float lb, int tid, bf16_t* ob, int ostr, int ocol) {
;     ...
;             const LAS unsigned char* vp = lds + HG_VV + (sb * 32 + quad * 4 + (fr >> 2)) * 288 + (wv * 16 + (fr & 3) * 4) * 2;
;             const bf16x8 vf = cat8(ldtr(vp), ldtr(vp + 16 * 288));
; #pragma unroll
;             for (int tt = 0; tt < 4; ++tt) if (tt >= 2 * sb) o[tt] = mfma16(vf, pack8(at[0][tt], at[1][tt]), o[tt]);
;         }
; #pragma unroll
;         for (int kt = 0; kt < 8; ++kt) { const float eb = ((const LAS float*)(lds + HG_EBT))[kt * 16 + fr]; st[kt] = st[kt] * eb; }
; #pragma unroll
;         for (int tb = 0; tb < 2; ++tb) {
;             const LAS unsigned char* vp = lds + HG_VV + (tb * 32 + quad * 8 + (fr >> 2)) * 288 + (wv * 16 + (fr & 3) * 4) * 2;
;             const bf16x8 vf = cat8(ldtr(vp), ldtr(vp + 4 * 288));
; #pragma unroll
;             for (int kt = 0; kt < 8; ++kt) { const bf16x8 kb = *(const LAS bf16x8*)(lds + HG_KET + (kt * 16 + fr) * 144 + (tb * 32 + quad * 8) * 2); st[kt] = mfma16(vf, kb, st[kt]); }
;         }
; #pragma unroll
;         for (int tt = 0; tt < 4; ++tt) { u32x2 w; w.x = pk2(o[tt][0], o[tt][1]); w.y = pk2(o[tt][2], o[tt][3]);
;             *(u32x2*)(ob + (size_t)hg_row(bl, dir, c, tt * 16 + fr) * ostr + ocol + wv * 16 + quad * 4) = w; }
	v_mfma_f32_16x16x32_bf16 v[72:75], v[118:121], v[72:75], 0
	v_mfma_f32_16x16x32_bf16 v[118:121], v[118:121], v[68:71], 0
	s_waitcnt lgkmcnt(0)
	v_mfma_f32_16x16x32_bf16 v[68:71], v[122:125], v[68:71], 0
	ds_read_b128 v[122:125], v114 offset:64
	ds_read_b128 v[126:129], v114 offset:4416
	ds_read_b128 v[130:133], v114 offset:17472
	s_waitcnt lgkmcnt(0)
	v_mfma_f32_16x16x32_bf16 v[72:75], v[130:133], v[122:125], v[72:75]
	ds_read_b128 v[122:125], v114 offset:21824
	v_mfma_f32_16x16x32_bf16 v[118:121], v[130:133], v[126:129], v[118:121]
	s_waitcnt lgkmcnt(0)
	v_mfma_f32_16x16x32_bf16 v[68:71], v[122:125], v[126:129], v[68:71]
	ds_read_b128 v[122:125], v114 offset:128
	ds_read_b128 v[126:129], v114 offset:4480
	ds_read_b128 v[130:133], v114 offset:17536
	s_waitcnt lgkmcnt(0)
	v_mfma_f32_16x16x32_bf16 v[72:75], v[130:133], v[122:125], v[72:75]
	ds_read_b128 v[122:125], v114 offset:21888
	v_mfma_f32_16x16x32_bf16 v[118:121], v[130:133], v[126:129], v[118:121]
	s_waitcnt lgkmcnt(0)
	v_mfma_f32_16x16x32_bf16 v[122:125], v[122:125], v[126:129], v[68:71]
	s_nop 2
	ds_read_b128 v[68:71], v114 offset:192
	ds_read_b128 v[126:129], v114 offset:4544
	ds_read_b128 v[130:133], v114 offset:17600
	s_waitcnt lgkmcnt(0)
	v_mfma_f32_16x16x32_bf16 v[72:75], v[130:133], v[68:71], v[72:75]
	v_mfma_f32_16x16x32_bf16 v[68:71], v[130:133], v[126:129], v[118:121]
	s_nop 6
	v_cndmask_b32_e64 v0, v72, 0, s[50:51]
	v_cndmask_b32_e64 v1, 0, v73, s[52:53]
	v_cndmask_b32_e64 v3, v74, 0, s[54:55]
	ds_read_b128 v[118:121], v114 offset:21952
	s_waitcnt lgkmcnt(0)
	v_mfma_f32_16x16x32_bf16 v[118:121], v[118:121], v[126:129], v[122:125]
	v_cndmask_b32_e64 v72, v75, 0, s[56:57]
	v_cvt_pk_bf16_f32 v0, v0, v1
	v_cvt_pk_bf16_f32 v1, v3, v72
	s_nop 4
	v_cndmask_b32_e64 v122, v118, 0, s[50:51]
	v_cndmask_b32_e64 v123, 0, v119, s[52:53]
	v_cndmask_b32_e64 v124, v120, 0, s[54:55]
	v_cndmask_b32_e64 v125, v121, 0, s[56:57]
	ds_read_b64_tr_b16 v[118:119], v97 offset:62464
	ds_read_b64_tr_b16 v[120:121], v98 offset:13824
	v_mov_b32_e32 v3, v2
	v_cvt_pk_bf16_f32 v68, v68, v69
	v_cvt_pk_bf16_f32 v69, v70, v71
	s_waitcnt lgkmcnt(0)
	v_mfma_f32_16x16x32_bf16 v[72:75], v[118:121], v[0:3], v[80:83]
	ds_read2_b32 v[126:127], v95 offset1:16
	ds_read2_b32 v[128:129], v95 offset0:32 offset1:48
	ds_read2_b32 v[132:133], v95 offset0:64 offset1:80
	ds_read2_b32 v[134:135], v95 offset0:96 offset1:112
	ds_read_b64_tr_b16 v[152:153], v115 offset:53248
	ds_read_b64_tr_b16 v[154:155], v115 offset:54400
	v_add_u32_e32 v136, v94, v99
	v_cvt_pk_bf16_f32 v70, v122, v123
	v_cvt_pk_bf16_f32 v71, v124, v125
	ds_read_b128 v[192:195], v136 offset:34816
	ds_read_b128 v[196:199], v136 offset:37120
	ds_read_b128 v[200:203], v136 offset:39424
	ds_read_b128 v[204:207], v136 offset:41728
	ds_read_b128 v[208:211], v136 offset:44032
	ds_read_b128 v[212:215], v136 offset:46336
	ds_read_b128 v[216:219], v136 offset:48640
	ds_read_b128 v[220:223], v136 offset:50944
	v_add_u32_e32 v3, s63, v91
	s_add_i32 s63, s63, 64
	v_mfma_f32_16x16x32_bf16 v[68:71], v[118:121], v[68:71], v[76:79]
	v_cvt_pk_bf16_f32 v138, v64, v65
	v_cvt_pk_bf16_f32 v139, v66, v67
	v_add_u32_e32 v172, 48, v100
	v_cndmask_b32_e32 v172, v172, v3, vcc
	v_add_u32_e32 v172, s62, v172
	v_mad_i64_i32 v[144:145], s[14:15], v172, s8, v[88:89]
	v_cvt_pk_bf16_f32 v140, v60, v61
	v_cvt_pk_bf16_f32 v141, v62, v63
	v_add_u32_e32 v172, 16, v3
	v_add_u32_e32 v173, 32, v100
	v_cndmask_b32_e32 v172, v173, v172, vcc
	v_add_u32_e32 v172, s62, v172
	global_store_dwordx2 v[144:145], v[138:139], off
	v_mad_i64_i32 v[146:147], s[14:15], v172, s8, v[88:89]
	v_cvt_pk_bf16_f32 v142, v72, v73
	v_cvt_pk_bf16_f32 v143, v74, v75
	v_add_u32_e32 v172, 32, v3
	v_add_u32_e32 v173, 16, v100
	v_cndmask_b32_e32 v172, v173, v172, vcc
	v_add_u32_e32 v172, s62, v172
	global_store_dwordx2 v[146:147], v[140:141], off
	v_mad_i64_i32 v[168:169], s[14:15], v172, s8, v[88:89]
	v_add_u32_e32 v3, 48, v3
	v_cndmask_b32_e32 v3, v100, v3, vcc
	v_add_u32_e32 v3, s62, v3
	global_store_dwordx2 v[168:169], v[142:143], off
	v_mad_i64_i32 v[170:171], s[14:15], v3, s8, v[88:89]
	v_subrev_u32_e32 v100, 64, v100
	s_waitcnt lgkmcnt(10)
	v_pk_mul_f32 v[6:7], v[6:7], v[126:127] op_sel_hi:[1,0]
	v_pk_mul_f32 v[4:5], v[4:5], v[126:127] op_sel_hi:[1,0]
	v_mov_b32_e32 v126, v127
	v_pk_mul_f32 v[58:59], v[58:59], v[126:127] op_sel_hi:[1,0]
	v_pk_mul_f32 v[56:57], v[56:57], v[126:127] op_sel_hi:[1,0]
	v_pk_mul_f32 v[50:51], v[50:51], v[128:129] op_sel_hi:[1,0]
	v_pk_mul_f32 v[48:49], v[48:49], v[128:129] op_sel_hi:[1,0]
	v_mov_b32_e32 v128, v129
	v_pk_mul_f32 v[54:55], v[54:55], v[128:129] op_sel_hi:[1,0]
	v_pk_mul_f32 v[52:53], v[52:53], v[128:129] op_sel_hi:[1,0]
	v_pk_mul_f32 v[42:43], v[42:43], v[132:133] op_sel_hi:[1,0]
	v_pk_mul_f32 v[40:41], v[40:41], v[132:133] op_sel_hi:[1,0]
	v_mov_b32_e32 v132, v133
	v_pk_mul_f32 v[46:47], v[46:47], v[132:133] op_sel_hi:[1,0]
	v_pk_mul_f32 v[44:45], v[44:45], v[132:133] op_sel_hi:[1,0]
	v_pk_mul_f32 v[38:39], v[38:39], v[134:135] op_sel_hi:[1,0]
	v_pk_mul_f32 v[36:37], v[36:37], v[134:135] op_sel_hi:[1,0]
	v_mov_b32_e32 v134, v135
	v_pk_mul_f32 v[34:35], v[34:35], v[134:135] op_sel_hi:[1,0]
	v_pk_mul_f32 v[32:33], v[32:33], v[134:135] op_sel_hi:[1,0]
	v_cvt_pk_bf16_f32 v148, v68, v69
	v_cvt_pk_bf16_f32 v149, v70, v71
	global_store_dwordx2 v[170:171], v[148:149], off
	s_waitcnt lgkmcnt(7)
	v_mfma_f32_16x16x32_bf16 v[4:7], v[152:155], v[192:195], v[4:7]
	ds_read_b64_tr_b16 v[156:157], v116 offset:53248
	s_waitcnt lgkmcnt(7)
	v_mfma_f32_16x16x32_bf16 v[56:59], v[152:155], v[196:199], v[56:59]
	ds_read_b64_tr_b16 v[158:159], v116 offset:54400
	s_waitcnt lgkmcnt(7)
; #define LAS __attribute__((address_space(3)))
; __device__ __forceinline__ unsigned short f2bf(float f) { return (unsigned short)(pk2(f, 0.f) & 0xffffu); }
; __device__ __forceinline__ float bf2f(unsigned short h) { return __uint_as_float(((unsigned)h) << 16); }
; __device__ __forceinline__ float fexp2(float x) { return __builtin_amdgcn_exp2f(x); }
; __device__ __forceinline__ float flog2(float x) { return __builtin_amdgcn_logf(x); }
; __device__ __forceinline__ float frcp(float x) { return __builtin_amdgcn_rcpf(x); }
; __device__ __forceinline__ void hgrn_unit(LAS unsigned char* lds, bf16_t* zC, int bl, int h, int dir, float lb, int tid, bf16_t* ob, int ostr, int ocol) {
;     ...
;         for (int j = 0; j < 2; ++j) { const int id = tid + j * 512; *(LAS u32x4*)(lds + HG_QE + (id >> 4) * 272 + (id & 15) * 16) = qp_[j]; *(LAS u32x4*)(lds + HG_KN + (id >> 4) * 272 + (id & 15) * 16) = fp_[j];
;             *(LAS u32x4*)(lds + HG_VV + (id >> 4) * 288 + (id & 15) * 16) = vp_[j]; }
;         __syncthreads();
;         float bl_[16], kk_[16]; float run = 0.f;
; #pragma unroll
;         for (int i = 0; i < 16; ++i) {
;             const float f = bf2f(*(const LAS unsigned short*)(lds + HG_KN + (tq * 16 + i) * 272 + k * 2));
;             const float sg = frcp(1.f + fexp2(-LOG2E * f));
;             const float fg = lb + oml * sg;
;             const float g2 = fmaxf(flog2(fg), -100.f);
;             run += g2; bl_[i] = run; kk_[i] = oml * (1.f - sg);
;         }
;         ((LAS float*)(lds + HG_SUB))[tq * 128 + k] = run;
; #pragma unroll
;         for (int kt = 0; kt < 8; ++kt)
; #pragma unroll
;             for (int j = 0; j < 4; ++j) *(LAS unsigned short*)(lds + HG_STB + (wv * 16 + quad * 4 + j) * 272 + (kt * 16 + fr) * 2) = f2bf(st[kt][j]);
;     ...
;         for (int kt = 0; kt < 8; ++kt) { const float eb = ((const LAS float*)(lds + HG_EBT))[kt * 16 + fr]; st[kt] = st[kt] * eb; }
; #pragma unroll
;         for (int tb = 0; tb < 2; ++tb) {
;             const LAS unsigned char* vp = lds + HG_VV + (tb * 32 + quad * 8 + (fr >> 2)) * 288 + (wv * 16 + (fr & 3) * 4) * 2;
;             const bf16x8 vf = cat8(ldtr(vp), ldtr(vp + 4 * 288));
; #pragma unroll
;             for (int kt = 0; kt < 8; ++kt) { const bf16x8 kb = *(const LAS bf16x8*)(lds + HG_KET + (kt * 16 + fr) * 144 + (tb * 32 + quad * 8) * 2); st[kt] = mfma16(vf, kb, st[kt]); }
;         }
	v_mfma_f32_16x16x32_bf16 v[48:51], v[152:155], v[200:203], v[48:51]
	ds_read_b128 v[224:227], v117 offset:34816
	s_waitcnt lgkmcnt(7)
	v_mfma_f32_16x16x32_bf16 v[52:55], v[152:155], v[204:207], v[52:55]
	ds_read_b128 v[228:231], v117 offset:37120
	s_waitcnt lgkmcnt(7)
	v_mfma_f32_16x16x32_bf16 v[40:43], v[152:155], v[208:211], v[40:43]
	ds_read_b128 v[232:235], v117 offset:39424
	s_waitcnt lgkmcnt(7)
	v_mfma_f32_16x16x32_bf16 v[44:47], v[152:155], v[212:215], v[44:47]
	ds_read_b128 v[240:243], v117 offset:41728
	s_waitcnt lgkmcnt(7)
	v_mfma_f32_16x16x32_bf16 v[36:39], v[152:155], v[216:219], v[36:39]
	ds_read_b128 v[244:247], v117 offset:44032
	s_waitcnt lgkmcnt(7)
	v_mfma_f32_16x16x32_bf16 v[32:35], v[152:155], v[220:223], v[32:35]
	ds_read_b128 v[248:251], v117 offset:46336
	ds_read_b128 v[160:163], v117 offset:48640
	ds_read_b128 v[164:167], v117 offset:50944
	s_waitcnt lgkmcnt(7)
	v_mfma_f32_16x16x32_bf16 v[4:7], v[156:159], v[224:227], v[4:7]
	s_waitcnt lgkmcnt(6)
	v_mfma_f32_16x16x32_bf16 v[56:59], v[156:159], v[228:231], v[56:59]
	s_waitcnt lgkmcnt(5)
	v_mfma_f32_16x16x32_bf16 v[48:51], v[156:159], v[232:235], v[48:51]
	s_waitcnt lgkmcnt(4)
	v_mfma_f32_16x16x32_bf16 v[52:55], v[156:159], v[240:243], v[52:55]
	s_waitcnt lgkmcnt(3)
	v_mfma_f32_16x16x32_bf16 v[40:43], v[156:159], v[244:247], v[40:43]
	s_waitcnt lgkmcnt(2)
	v_mfma_f32_16x16x32_bf16 v[44:47], v[156:159], v[248:251], v[44:47]
	s_waitcnt lgkmcnt(1)
	v_mfma_f32_16x16x32_bf16 v[36:39], v[156:159], v[160:163], v[36:39]
	s_waitcnt lgkmcnt(0)
	v_mfma_f32_16x16x32_bf16 v[32:35], v[156:159], v[164:167], v[32:35]
	s_cmpk_eq_i32 s63, 0x800
	s_barrier
	s_cbranch_scc1 .LBB0_160
.LBB0_194:
	s_waitcnt vmcnt(5)
	ds_write_b128 v105, v[8:11]
	s_waitcnt vmcnt(3)
	ds_write_b128 v105, v[16:19] offset:17408
	ds_write_b128 v106, v[12:15] offset:53248
	s_waitcnt vmcnt(2)
	ds_write_b128 v107, v[20:23]
	s_waitcnt vmcnt(1)
	ds_write_b128 v107, v[24:27] offset:17408
	s_waitcnt vmcnt(0)
	ds_write_b128 v108, v[28:31] offset:53248
	s_waitcnt lgkmcnt(0)
	s_barrier
	ds_read_u16 v192, v109 offset:17408
	ds_read_u16 v193, v109 offset:17680
	ds_read_u16 v194, v109 offset:17952
	ds_read_u16 v195, v109 offset:18224
	ds_read_u16 v196, v109 offset:18496
	ds_read_u16 v197, v109 offset:18768
	ds_read_u16 v198, v109 offset:19040
	ds_read_u16 v199, v109 offset:19312
	ds_read_u16 v200, v109 offset:19584
	ds_read_u16 v201, v109 offset:19856
	ds_read_u16 v202, v109 offset:20128
	ds_read_u16 v203, v109 offset:20400
	ds_read_u16 v204, v109 offset:20672
	ds_read_u16 v205, v109 offset:20944
	ds_read_u16 v206, v109 offset:21216
	ds_read_u16 v207, v109 offset:21488
	v_cvt_pk_bf16_f32 v208, v4, s0
	v_cvt_pk_bf16_f32 v209, v5, s0
	v_cvt_pk_bf16_f32 v210, v6, s0
	v_cvt_pk_bf16_f32 v211, v7, s0
	v_cvt_pk_bf16_f32 v212, v56, s0
	v_cvt_pk_bf16_f32 v213, v57, s0
	v_cvt_pk_bf16_f32 v214, v58, s0
	v_cvt_pk_bf16_f32 v215, v59, s0
	ds_write_b16 v110, v208
	ds_write_b16 v110, v209 offset:272
	ds_write_b16 v110, v210 offset:544
	ds_write_b16 v110, v211 offset:816
	ds_write_b16 v110, v212 offset:32
	ds_write_b16 v110, v213 offset:304
	ds_write_b16 v110, v214 offset:576
	ds_write_b16 v110, v215 offset:848
	s_waitcnt lgkmcnt(8)
	v_lshlrev_b32_e32 v192, 16, v192
	v_lshlrev_b32_e32 v193, 16, v193
	v_lshlrev_b32_e32 v194, 16, v194
	v_lshlrev_b32_e32 v195, 16, v195
	v_lshlrev_b32_e32 v196, 16, v196
	v_cvt_pk_bf16_f32 v208, v48, s0
	v_lshlrev_b32_e32 v197, 16, v197
	v_lshlrev_b32_e32 v198, 16, v198
	ds_write_b16 v110, v208 offset:64
	v_lshlrev_b32_e32 v199, 16, v199
	v_lshlrev_b32_e32 v200, 16, v200
	v_lshlrev_b32_e32 v201, 16, v201
	v_cvt_pk_bf16_f32 v209, v49, s0
	v_lshlrev_b32_e32 v202, 16, v202
	v_lshlrev_b32_e32 v203, 16, v203
	ds_write_b16 v110, v209 offset:336
	v_lshlrev_b32_e32 v204, 16, v204
	v_lshlrev_b32_e32 v205, 16, v205
	v_lshlrev_b32_e32 v206, 16, v206
	v_cvt_pk_bf16_f32 v210, v50, s0
	v_lshlrev_b32_e32 v207, 16, v207
	v_mul_f32_e32 v192, 0xbfb8aa3b, v192
	ds_write_b16 v110, v210 offset:608
	v_mul_f32_e32 v193, 0xbfb8aa3b, v193
	v_mul_f32_e32 v194, 0xbfb8aa3b, v194
	v_mul_f32_e32 v195, 0xbfb8aa3b, v195
	v_cvt_pk_bf16_f32 v211, v51, s0
	v_mul_f32_e32 v196, 0xbfb8aa3b, v196
	v_mul_f32_e32 v197, 0xbfb8aa3b, v197
	ds_write_b16 v110, v211 offset:880
	v_mul_f32_e32 v198, 0xbfb8aa3b, v198
	v_mul_f32_e32 v199, 0xbfb8aa3b, v199
	v_mul_f32_e32 v200, 0xbfb8aa3b, v200
	v_cvt_pk_bf16_f32 v212, v52, s0
	v_mul_f32_e32 v201, 0xbfb8aa3b, v201
	v_mul_f32_e32 v202, 0xbfb8aa3b, v202
	ds_write_b16 v110, v212 offset:96
	v_mul_f32_e32 v203, 0xbfb8aa3b, v203
	v_mul_f32_e32 v204, 0xbfb8aa3b, v204
	v_mul_f32_e32 v205, 0xbfb8aa3b, v205
	v_cvt_pk_bf16_f32 v213, v53, s0
	v_mul_f32_e32 v206, 0xbfb8aa3b, v206
	v_mul_f32_e32 v207, 0xbfb8aa3b, v207
	ds_write_b16 v110, v213 offset:368
	v_exp_f32_e32 v192, v192
	v_exp_f32_e32 v193, v193
	v_exp_f32_e32 v194, v194
	v_cvt_pk_bf16_f32 v214, v54, s0
	v_exp_f32_e32 v195, v195
	v_exp_f32_e32 v196, v196
	ds_write_b16 v110, v214 offset:640
	v_exp_f32_e32 v197, v197
	v_exp_f32_e32 v198, v198
	v_exp_f32_e32 v199, v199
	v_cvt_pk_bf16_f32 v215, v55, s0
	v_exp_f32_e32 v200, v200
	v_exp_f32_e32 v201, v201
	ds_write_b16 v110, v215 offset:912
	v_exp_f32_e32 v202, v202
	v_exp_f32_e32 v203, v203
	v_exp_f32_e32 v204, v204
	v_cvt_pk_bf16_f32 v208, v40, s0
	v_exp_f32_e32 v205, v205
	v_exp_f32_e32 v206, v206
	ds_write_b16 v110, v208 offset:128
	v_exp_f32_e32 v207, v207
	v_add_f32_e32 v192, 1.0, v192
	v_add_f32_e32 v193, 1.0, v193
	v_cvt_pk_bf16_f32 v209, v41, s0
	v_add_f32_e32 v194, 1.0, v194
	v_add_f32_e32 v195, 1.0, v195
	ds_write_b16 v110, v209 offset:400
	v_add_f32_e32 v196, 1.0, v196
	v_add_f32_e32 v197, 1.0, v197
; #define LAS __attribute__((address_space(3)))
; __device__ __forceinline__ unsigned short f2bf(float f) { return (unsigned short)(pk2(f, 0.f) & 0xffffu); }
; __device__ __forceinline__ float bf2f(unsigned short h) { return __uint_as_float(((unsigned)h) << 16); }
; __device__ __forceinline__ float fexp2(float x) { return __builtin_amdgcn_exp2f(x); }
; __device__ __forceinline__ float flog2(float x) { return __builtin_amdgcn_logf(x); }
; __device__ __forceinline__ float frcp(float x) { return __builtin_amdgcn_rcpf(x); }
; __device__ __forceinline__ void hgrn_unit(LAS unsigned char* lds, bf16_t* zC, int bl, int h, int dir, float lb, int tid, bf16_t* ob, int ostr, int ocol) {
;     ...
;         for (int i = 0; i < 16; ++i) {
;             const float f = bf2f(*(const LAS unsigned short*)(lds + HG_KN + (tq * 16 + i) * 272 + k * 2));
;             const float sg = frcp(1.f + fexp2(-LOG2E * f));
;             const float fg = lb + oml * sg;
;             const float g2 = fmaxf(flog2(fg), -100.f);
;             run += g2; bl_[i] = run; kk_[i] = oml * (1.f - sg);
;         }
;         ((LAS float*)(lds + HG_SUB))[tq * 128 + k] = run;
; #pragma unroll
;         for (int kt = 0; kt < 8; ++kt)
; #pragma unroll
;             for (int j = 0; j < 4; ++j) *(LAS unsigned short*)(lds + HG_STB + (wv * 16 + quad * 4 + j) * 272 + (kt * 16 + fr) * 2) = f2bf(st[kt][j]);
;         __syncthreads();
	v_add_f32_e32 v198, 1.0, v198
	v_cvt_pk_bf16_f32 v210, v42, s0
	v_add_f32_e32 v199, 1.0, v199
	v_add_f32_e32 v200, 1.0, v200
	ds_write_b16 v110, v210 offset:672
	v_add_f32_e32 v201, 1.0, v201
	v_add_f32_e32 v202, 1.0, v202
	v_add_f32_e32 v203, 1.0, v203
	v_cvt_pk_bf16_f32 v211, v43, s0
	v_add_f32_e32 v204, 1.0, v204
	v_add_f32_e32 v205, 1.0, v205
	ds_write_b16 v110, v211 offset:944
	v_add_f32_e32 v206, 1.0, v206
	v_add_f32_e32 v207, 1.0, v207
	v_rcp_f32_e32 v68, v192
	v_cvt_pk_bf16_f32 v212, v44, s0
	v_rcp_f32_e32 v69, v193
	v_rcp_f32_e32 v72, v194
	ds_write_b16 v110, v212 offset:160
	v_rcp_f32_e32 v73, v195
	v_rcp_f32_e32 v74, v196
	v_rcp_f32_e32 v75, v197
	v_cvt_pk_bf16_f32 v213, v45, s0
	v_rcp_f32_e32 v60, v198
	v_rcp_f32_e32 v61, v199
	ds_write_b16 v110, v213 offset:432
	v_rcp_f32_e32 v70, v200
	v_rcp_f32_e32 v71, v201
	v_rcp_f32_e32 v66, v202
	v_cvt_pk_bf16_f32 v214, v46, s0
	v_rcp_f32_e32 v67, v203
	v_rcp_f32_e32 v64, v204
	ds_write_b16 v110, v214 offset:704
	v_rcp_f32_e32 v65, v205
	v_rcp_f32_e32 v0, v206
	v_rcp_f32_e32 v1, v207
	v_cvt_pk_bf16_f32 v215, v47, s0
	v_fma_f32 v192, v86, v68, v90
	v_fma_f32 v193, v86, v69, v90
	ds_write_b16 v110, v215 offset:976
	v_fma_f32 v194, v86, v72, v90
	v_fma_f32 v195, v86, v73, v90
	v_fma_f32 v196, v86, v74, v90
	v_cvt_pk_bf16_f32 v208, v36, s0
	v_fma_f32 v197, v86, v75, v90
	v_fma_f32 v198, v86, v60, v90
	ds_write_b16 v110, v208 offset:192
	v_fma_f32 v199, v86, v61, v90
	v_fma_f32 v200, v86, v70, v90
	v_fma_f32 v201, v86, v71, v90
	v_cvt_pk_bf16_f32 v209, v37, s0
	v_fma_f32 v202, v86, v66, v90
	v_fma_f32 v203, v86, v67, v90
	ds_write_b16 v110, v209 offset:464
	v_fma_f32 v204, v86, v64, v90
	v_fma_f32 v205, v86, v65, v90
	v_fma_f32 v206, v86, v0, v90
	v_cvt_pk_bf16_f32 v210, v38, s0
	v_fma_f32 v207, v86, v1, v90
	v_log_f32_e32 v192, v192
	ds_write_b16 v110, v210 offset:736
	v_log_f32_e32 v193, v193
	v_log_f32_e32 v194, v194
	v_log_f32_e32 v195, v195
	v_cvt_pk_bf16_f32 v211, v39, s0
	v_log_f32_e32 v196, v196
	v_log_f32_e32 v197, v197
	ds_write_b16 v110, v211 offset:1008
	v_log_f32_e32 v198, v198
	v_log_f32_e32 v199, v199
	v_log_f32_e32 v200, v200
	v_cvt_pk_bf16_f32 v212, v32, s0
	v_log_f32_e32 v201, v201
	v_log_f32_e32 v202, v202
	ds_write_b16 v110, v212 offset:224
	v_log_f32_e32 v203, v203
	v_log_f32_e32 v204, v204
	v_log_f32_e32 v205, v205
	v_cvt_pk_bf16_f32 v213, v33, s0
	v_log_f32_e32 v206, v206
	v_log_f32_e32 v207, v207
	ds_write_b16 v110, v213 offset:496
	v_pk_add_f32 v[68:69], v[68:69], 1.0 op_sel_hi:[1,0] neg_lo:[1,0] neg_hi:[1,0]
	v_pk_add_f32 v[72:73], v[72:73], 1.0 op_sel_hi:[1,0] neg_lo:[1,0] neg_hi:[1,0]
	v_pk_add_f32 v[74:75], v[74:75], 1.0 op_sel_hi:[1,0] neg_lo:[1,0] neg_hi:[1,0]
	v_cvt_pk_bf16_f32 v214, v34, s0
	v_pk_add_f32 v[60:61], v[60:61], 1.0 op_sel_hi:[1,0] neg_lo:[1,0] neg_hi:[1,0]
	v_pk_add_f32 v[70:71], v[70:71], 1.0 op_sel_hi:[1,0] neg_lo:[1,0] neg_hi:[1,0]
	ds_write_b16 v110, v214 offset:768
	v_pk_add_f32 v[66:67], v[66:67], 1.0 op_sel_hi:[1,0] neg_lo:[1,0] neg_hi:[1,0]
	v_pk_add_f32 v[64:65], v[64:65], 1.0 op_sel_hi:[1,0] neg_lo:[1,0] neg_hi:[1,0]
	v_max_f32_e32 v192, 0xc2c80000, v192
	v_cvt_pk_bf16_f32 v215, v35, s0
	v_max_f32_e32 v193, 0xc2c80000, v193
	v_max_f32_e32 v194, 0xc2c80000, v194
	ds_write_b16 v110, v215 offset:1040
	v_max_f32_e32 v195, 0xc2c80000, v195
	v_max_f32_e32 v196, 0xc2c80000, v196
	v_max_f32_e32 v197, 0xc2c80000, v197
	v_max_f32_e32 v198, 0xc2c80000, v198
	v_max_f32_e32 v199, 0xc2c80000, v199
	v_max_f32_e32 v200, 0xc2c80000, v200
	v_max_f32_e32 v201, 0xc2c80000, v201
	v_max_f32_e32 v202, 0xc2c80000, v202
	v_max_f32_e32 v203, 0xc2c80000, v203
	v_max_f32_e32 v204, 0xc2c80000, v204
	v_max_f32_e32 v205, 0xc2c80000, v205
	v_max_f32_e32 v206, 0xc2c80000, v206
	v_max_f32_e32 v207, 0xc2c80000, v207
	v_add_f32_e32 v62, 0, v192
	v_add_f32_e32 v123, v62, v193
	v_add_f32_e32 v122, v123, v194
	v_add_f32_e32 v121, v122, v195
	v_add_f32_e32 v120, v121, v196
	v_add_f32_e32 v79, v120, v197
	v_add_f32_e32 v78, v79, v198
	v_add_f32_e32 v124, v78, v199
	v_add_f32_e32 v83, v124, v200
	v_add_f32_e32 v119, v83, v201
	v_add_f32_e32 v118, v119, v202
	v_add_f32_e32 v82, v118, v203
	v_add_f32_e32 v81, v82, v204
	v_add_f32_e32 v80, v81, v205
	v_add_f32_e32 v3, v80, v206
	v_add_f32_e32 v127, v3, v207
	ds_write_b32 v92, v127
	s_waitcnt lgkmcnt(0)
	s_barrier
; #define LAS __attribute__((address_space(3)))
; __device__ __forceinline__ unsigned pk2(float lo, float hi) { f32x2 v = {lo, hi}; bf16x2_t b = __builtin_convertvector(v, bf16x2_t); return __builtin_bit_cast(unsigned, b); }
; __device__ __forceinline__ unsigned short f2bf(float f) { return (unsigned short)(pk2(f, 0.f) & 0xffffu); }
; __device__ __forceinline__ float bf2f(unsigned short h) { return __uint_as_float(((unsigned)h) << 16); }
; __device__ __forceinline__ float fexp2(float x) { return __builtin_amdgcn_exp2f(x); }
; __device__ __forceinline__ void hgrn_unit(LAS unsigned char* lds, bf16_t* zC, int bl, int h, int dir, float lb, int tid, bf16_t* ob, int ostr, int ocol) {
;     ...
;             const LAS float* SUB = (const LAS float*)(lds + HG_SUB);
;             const float s0 = SUB[k], s1 = SUB[128 + k], s2 = SUB[256 + k], s3 = SUB[384 + k];
;             const float bn = (tq > 0 ? s0 : 0.f) + (tq > 1 ? s1 : 0.f) + (tq > 2 ? s2 : 0.f);
;             const float btot = (s0 + s1) + (s2 + s3);
;             float ke_[16];
; #pragma unroll
;             for (int i = 0; i < 16; ++i) {
;                 const float bc = bn + bl_[i];
;                 const float q = bf2f(*(const LAS unsigned short*)(lds + HG_QE + (tq * 16 + i) * 272 + k * 2));
;                 const float qe = q * fexp2(bc);
;                 const float kn = kk_[i] * fexp2(fminf(-bc, 110.f));
;                 ke_[i] = kk_[i] * fexp2(btot - bc);
;                 *(LAS unsigned short*)(lds + HG_QE + (tq * 16 + i) * 272 + k * 2) = f2bf(qe);
;                 *(LAS unsigned short*)(lds + HG_KN + (tq * 16 + i) * 272 + k * 2) = f2bf(kn);
;             }
;             u32x4 w0, w1;
;             w0.x = pk2(ke_[0], ke_[1]); w0.y = pk2(ke_[2], ke_[3]); w0.z = pk2(ke_[4], ke_[5]); w0.w = pk2(ke_[6], ke_[7]);
;             w1.x = pk2(ke_[8], ke_[9]); w1.y = pk2(ke_[10], ke_[11]); w1.z = pk2(ke_[12], ke_[13]); w1.w = pk2(ke_[14], ke_[15]);
;             *(LAS u32x4*)(lds + HG_KET + k * 144 + tq * 32) = w0; *(LAS u32x4*)(lds + HG_KET + k * 144 + tq * 32 + 16) = w1;
;             if (tq == 0) ((LAS float*)(lds + HG_EBT))[k] = fexp2(btot);
	ds_read2st64_b32 v[76:77], v93 offset1:2
	ds_read2st64_b32 v[128:129], v93 offset0:4 offset1:6
	ds_read_u16 v192, v109
	ds_read_u16 v193, v109 offset:272
	ds_read_u16 v194, v109 offset:544
	ds_read_u16 v195, v109 offset:816
	ds_read_u16 v196, v109 offset:1088
	ds_read_u16 v197, v109 offset:1360
	ds_read_u16 v198, v109 offset:1632
	ds_read_u16 v199, v109 offset:1904
	ds_read_u16 v200, v109 offset:2176
	ds_read_u16 v201, v109 offset:2448
	ds_read_u16 v202, v109 offset:2720
	ds_read_u16 v203, v109 offset:2992
	ds_read_u16 v204, v109 offset:3264
	ds_read_u16 v205, v109 offset:3536
	ds_read_u16 v206, v109 offset:3808
	ds_read_u16 v207, v109 offset:4080
	v_pk_add_f32 v[0:1], v[0:1], 1.0 op_sel_hi:[1,0] neg_lo:[1,0] neg_hi:[1,0]
	v_pk_mul_f32 v[68:69], v[86:87], v[68:69]
	v_pk_mul_f32 v[72:73], v[86:87], v[72:73]
	v_pk_mul_f32 v[74:75], v[86:87], v[74:75]
	v_pk_mul_f32 v[60:61], v[86:87], v[60:61]
	v_pk_mul_f32 v[70:71], v[86:87], v[70:71]
	v_pk_mul_f32 v[66:67], v[86:87], v[66:67]
	v_pk_mul_f32 v[64:65], v[86:87], v[64:65]
	v_pk_mul_f32 v[0:1], v[86:87], v[0:1]
	s_waitcnt lgkmcnt(15)
	v_cndmask_b32_e64 v63, 0, v76, s[42:43]
	v_cndmask_b32_e64 v125, 0, v77, s[44:45]
	v_cndmask_b32_e64 v133, 0, v128, s[46:47]
	v_add_f32_e32 v131, v63, v125
	v_add_f32_e32 v126, v76, v77
	v_add_f32_e32 v130, v128, v129
	v_add_f32_e32 v209, v131, v133
	v_add_f32_e32 v208, v126, v130
	v_add_f32_e32 v210, v62, v209
	v_add_f32_e32 v211, v123, v209
	v_add_f32_e32 v212, v122, v209
	v_add_f32_e32 v213, v121, v209
	v_add_f32_e32 v214, v120, v209
	v_add_f32_e32 v215, v79, v209
	v_add_f32_e32 v216, v78, v209
	v_add_f32_e32 v217, v124, v209
	v_add_f32_e32 v218, v83, v209
	v_add_f32_e32 v219, v119, v209
	v_add_f32_e32 v220, v118, v209
	v_add_f32_e32 v221, v82, v209
	v_add_f32_e32 v222, v81, v209
	v_add_f32_e32 v223, v80, v209
	v_add_f32_e32 v224, v3, v209
	v_add_f32_e32 v225, v127, v209
	v_exp_f32_e32 v226, v210
	v_exp_f32_e32 v227, v211
	v_exp_f32_e32 v228, v212
	v_exp_f32_e32 v229, v213
	v_exp_f32_e32 v230, v214
	v_exp_f32_e32 v231, v215
	v_exp_f32_e32 v232, v216
	v_exp_f32_e32 v233, v217
	v_min_f32_e64 v234, -v210, s36
	v_min_f32_e64 v235, -v211, s36
	v_min_f32_e64 v236, -v212, s36
	v_min_f32_e64 v237, -v213, s36
	v_min_f32_e64 v248, -v214, s36
	v_min_f32_e64 v249, -v215, s36
	v_min_f32_e64 v250, -v216, s36
	v_min_f32_e64 v251, -v217, s36
	v_sub_f32_e32 v240, v208, v210
	v_sub_f32_e32 v241, v208, v211
	v_sub_f32_e32 v242, v208, v212
	v_sub_f32_e32 v243, v208, v213
	v_sub_f32_e32 v244, v208, v214
	v_sub_f32_e32 v245, v208, v215
	v_sub_f32_e32 v246, v208, v216
	v_sub_f32_e32 v247, v208, v217
	v_exp_f32_e32 v234, v234
	v_exp_f32_e32 v235, v235
	v_exp_f32_e32 v236, v236
	v_exp_f32_e32 v237, v237
	v_exp_f32_e32 v248, v248
	v_exp_f32_e32 v249, v249
	v_exp_f32_e32 v250, v250
	v_exp_f32_e32 v251, v251
	s_waitcnt lgkmcnt(8)
	v_lshlrev_b32_e32 v192, 16, v192
	v_lshlrev_b32_e32 v193, 16, v193
	v_lshlrev_b32_e32 v194, 16, v194
	v_lshlrev_b32_e32 v195, 16, v195
	v_lshlrev_b32_e32 v196, 16, v196
	v_lshlrev_b32_e32 v197, 16, v197
	v_lshlrev_b32_e32 v198, 16, v198
	v_lshlrev_b32_e32 v199, 16, v199
	v_exp_f32_e32 v240, v240
	v_exp_f32_e32 v241, v241
	v_exp_f32_e32 v242, v242
	v_exp_f32_e32 v243, v243
	v_exp_f32_e32 v244, v244
	v_exp_f32_e32 v245, v245
	v_exp_f32_e32 v246, v246
	v_exp_f32_e32 v247, v247
	v_mul_f32_e32 v192, v226, v192
	v_mul_f32_e32 v193, v227, v193
	v_mul_f32_e32 v194, v228, v194
	v_mul_f32_e32 v195, v229, v195
	v_mul_f32_e32 v196, v230, v196
	v_mul_f32_e32 v197, v231, v197
	v_mul_f32_e32 v198, v232, v198
	v_mul_f32_e32 v199, v233, v199
	v_mul_f32_e32 v234, v68, v234
	v_mul_f32_e32 v235, v69, v235
	v_mul_f32_e32 v236, v72, v236
	v_mul_f32_e32 v237, v73, v237
	v_mul_f32_e32 v248, v74, v248
	v_mul_f32_e32 v249, v75, v249
	v_mul_f32_e32 v250, v60, v250
	v_mul_f32_e32 v251, v61, v251
	v_cvt_pk_bf16_f32 v192, v192, s0
	v_cvt_pk_bf16_f32 v193, v193, s0
	v_cvt_pk_bf16_f32 v194, v194, s0
	v_cvt_pk_bf16_f32 v195, v195, s0
	v_cvt_pk_bf16_f32 v196, v196, s0
	v_cvt_pk_bf16_f32 v197, v197, s0
	v_cvt_pk_bf16_f32 v198, v198, s0
	v_cvt_pk_bf16_f32 v199, v199, s0
	v_cvt_pk_bf16_f32 v234, v234, s0
	ds_write_b16 v109, v192
	v_cvt_pk_bf16_f32 v235, v235, s0
	ds_write_b16 v109, v193 offset:272
	v_cvt_pk_bf16_f32 v236, v236, s0
	ds_write_b16 v109, v194 offset:544
	v_cvt_pk_bf16_f32 v237, v237, s0
	ds_write_b16 v109, v195 offset:816
	v_cvt_pk_bf16_f32 v248, v248, s0
	ds_write_b16 v109, v196 offset:1088
	v_cvt_pk_bf16_f32 v249, v249, s0
	ds_write_b16 v109, v197 offset:1360
	v_cvt_pk_bf16_f32 v250, v250, s0
	ds_write_b16 v109, v198 offset:1632
	v_cvt_pk_bf16_f32 v251, v251, s0
	ds_write_b16 v109, v199 offset:1904
	v_pk_mul_f32 v[68:69], v[68:69], v[240:241]
	ds_write_b16 v109, v234 offset:17408
	ds_write_b16 v109, v235 offset:17680
	v_pk_mul_f32 v[72:73], v[72:73], v[242:243]
	ds_write_b16 v109, v236 offset:17952
	ds_write_b16 v109, v237 offset:18224
	v_pk_mul_f32 v[74:75], v[74:75], v[244:245]
	ds_write_b16 v109, v248 offset:18496
	ds_write_b16 v109, v249 offset:18768
	v_pk_mul_f32 v[60:61], v[60:61], v[246:247]
	ds_write_b16 v109, v250 offset:19040
	ds_write_b16 v109, v251 offset:19312
	v_exp_f32_e32 v226, v218
	v_exp_f32_e32 v227, v219
	v_exp_f32_e32 v228, v220
	v_exp_f32_e32 v229, v221
	v_exp_f32_e32 v230, v222
	v_exp_f32_e32 v231, v223
	v_exp_f32_e32 v232, v224
	v_exp_f32_e32 v233, v225
	v_min_f32_e64 v234, -v218, s36
	v_min_f32_e64 v235, -v219, s36
	v_min_f32_e64 v236, -v220, s36
	v_min_f32_e64 v237, -v221, s36
	v_min_f32_e64 v248, -v222, s36
	v_min_f32_e64 v249, -v223, s36
	v_min_f32_e64 v250, -v224, s36
	v_min_f32_e64 v251, -v225, s36
	v_sub_f32_e32 v240, v208, v218
	v_sub_f32_e32 v241, v208, v219
	v_sub_f32_e32 v242, v208, v220
	v_sub_f32_e32 v243, v208, v221
	v_sub_f32_e32 v244, v208, v222
	v_sub_f32_e32 v245, v208, v223
	v_sub_f32_e32 v246, v208, v224
	v_sub_f32_e32 v247, v208, v225
	v_exp_f32_e32 v234, v234
	v_exp_f32_e32 v235, v235
	v_exp_f32_e32 v236, v236
	v_exp_f32_e32 v237, v237
	v_exp_f32_e32 v248, v248
	v_exp_f32_e32 v249, v249
	v_exp_f32_e32 v250, v250
	v_exp_f32_e32 v251, v251
	s_waitcnt lgkmcnt(15)
; #define LAS __attribute__((address_space(3)))
; __device__ __forceinline__ unsigned pk2(float lo, float hi) { f32x2 v = {lo, hi}; bf16x2_t b = __builtin_convertvector(v, bf16x2_t); return __builtin_bit_cast(unsigned, b); }
; __device__ __forceinline__ unsigned short f2bf(float f) { return (unsigned short)(pk2(f, 0.f) & 0xffffu); }
; __device__ __forceinline__ float bf2f(unsigned short h) { return __uint_as_float(((unsigned)h) << 16); }
; __device__ __forceinline__ float fexp2(float x) { return __builtin_amdgcn_exp2f(x); }
; #define HG_PREFETCH(C) do { _Pragma("unroll") for (int j = 0; j < 2; ++j) { const int id = tid + j * 512; const bf16_t* rp_ = zC + (size_t)hg_row(bl, dir, (C), id >> 4) * 2560 + h * 128 + (id & 15) * 8; \
;         qp_[j] = *(const u32x4*)rp_; fp_[j] = *(const u32x4*)(rp_ + fcol - h * 128); vp_[j] = *(const u32x4*)(rp_ + 1536); } } while (0)
; __device__ __forceinline__ void hgrn_unit(LAS unsigned char* lds, bf16_t* zC, int bl, int h, int dir, float lb, int tid, bf16_t* ob, int ostr, int ocol) {
;     ...
;             for (int i = 0; i < 16; ++i) {
;                 const float bc = bn + bl_[i];
;                 const float q = bf2f(*(const LAS unsigned short*)(lds + HG_QE + (tq * 16 + i) * 272 + k * 2));
;                 const float qe = q * fexp2(bc);
;                 const float kn = kk_[i] * fexp2(fminf(-bc, 110.f));
;                 ke_[i] = kk_[i] * fexp2(btot - bc);
;                 *(LAS unsigned short*)(lds + HG_QE + (tq * 16 + i) * 272 + k * 2) = f2bf(qe);
;                 *(LAS unsigned short*)(lds + HG_KN + (tq * 16 + i) * 272 + k * 2) = f2bf(kn);
;             }
;             u32x4 w0, w1;
;             w0.x = pk2(ke_[0], ke_[1]); w0.y = pk2(ke_[2], ke_[3]); w0.z = pk2(ke_[4], ke_[5]); w0.w = pk2(ke_[6], ke_[7]);
;             w1.x = pk2(ke_[8], ke_[9]); w1.y = pk2(ke_[10], ke_[11]); w1.z = pk2(ke_[12], ke_[13]); w1.w = pk2(ke_[14], ke_[15]);
;             *(LAS u32x4*)(lds + HG_KET + k * 144 + tq * 32) = w0; *(LAS u32x4*)(lds + HG_KET + k * 144 + tq * 32 + 16) = w1;
;             if (tq == 0) ((LAS float*)(lds + HG_EBT))[k] = fexp2(btot);
;         }
;         __syncthreads();
;         if (c + 1 < 32) HG_PREFETCH(c + 1);
	v_lshlrev_b32_e32 v200, 16, v200
	v_lshlrev_b32_e32 v201, 16, v201
	v_lshlrev_b32_e32 v202, 16, v202
	v_lshlrev_b32_e32 v203, 16, v203
	v_lshlrev_b32_e32 v204, 16, v204
	v_lshlrev_b32_e32 v205, 16, v205
	v_lshlrev_b32_e32 v206, 16, v206
	v_lshlrev_b32_e32 v207, 16, v207
	v_exp_f32_e32 v240, v240
	v_exp_f32_e32 v241, v241
	v_exp_f32_e32 v242, v242
	v_exp_f32_e32 v243, v243
	v_exp_f32_e32 v244, v244
	v_exp_f32_e32 v245, v245
	v_exp_f32_e32 v246, v246
	v_exp_f32_e32 v247, v247
	v_mul_f32_e32 v200, v226, v200
	v_mul_f32_e32 v201, v227, v201
	v_mul_f32_e32 v202, v228, v202
	v_mul_f32_e32 v203, v229, v203
	v_mul_f32_e32 v204, v230, v204
	v_mul_f32_e32 v205, v231, v205
	v_mul_f32_e32 v206, v232, v206
	v_mul_f32_e32 v207, v233, v207
	v_mul_f32_e32 v234, v70, v234
	v_mul_f32_e32 v235, v71, v235
	v_mul_f32_e32 v236, v66, v236
	v_mul_f32_e32 v237, v67, v237
	v_mul_f32_e32 v248, v64, v248
	v_mul_f32_e32 v249, v65, v249
	v_mul_f32_e32 v250, v0, v250
	v_mul_f32_e32 v251, v1, v251
	v_cvt_pk_bf16_f32 v200, v200, s0
	v_cvt_pk_bf16_f32 v201, v201, s0
	v_cvt_pk_bf16_f32 v202, v202, s0
	v_cvt_pk_bf16_f32 v203, v203, s0
	v_cvt_pk_bf16_f32 v204, v204, s0
	v_cvt_pk_bf16_f32 v205, v205, s0
	v_cvt_pk_bf16_f32 v206, v206, s0
	v_cvt_pk_bf16_f32 v207, v207, s0
	v_cvt_pk_bf16_f32 v234, v234, s0
	ds_write_b16 v109, v200 offset:2176
	v_cvt_pk_bf16_f32 v235, v235, s0
	ds_write_b16 v109, v201 offset:2448
	v_cvt_pk_bf16_f32 v236, v236, s0
	ds_write_b16 v109, v202 offset:2720
	v_cvt_pk_bf16_f32 v237, v237, s0
	ds_write_b16 v109, v203 offset:2992
	v_cvt_pk_bf16_f32 v248, v248, s0
	ds_write_b16 v109, v204 offset:3264
	v_cvt_pk_bf16_f32 v249, v249, s0
	ds_write_b16 v109, v205 offset:3536
	v_cvt_pk_bf16_f32 v250, v250, s0
	ds_write_b16 v109, v206 offset:3808
	v_cvt_pk_bf16_f32 v251, v251, s0
	ds_write_b16 v109, v207 offset:4080
	v_pk_mul_f32 v[70:71], v[70:71], v[240:241]
	ds_write_b16 v109, v234 offset:19584
	ds_write_b16 v109, v235 offset:19856
	v_pk_mul_f32 v[66:67], v[66:67], v[242:243]
	ds_write_b16 v109, v236 offset:20128
	ds_write_b16 v109, v237 offset:20400
	v_pk_mul_f32 v[64:65], v[64:65], v[244:245]
	ds_write_b16 v109, v248 offset:20672
	ds_write_b16 v109, v249 offset:20944
	v_pk_mul_f32 v[0:1], v[0:1], v[246:247]
	ds_write_b16 v109, v250 offset:21216
	ds_write_b16 v109, v251 offset:21488
	v_cvt_pk_bf16_f32 v78, v68, v69
	v_cvt_pk_bf16_f32 v79, v72, v73
	v_cvt_pk_bf16_f32 v80, v74, v75
	v_cvt_pk_bf16_f32 v81, v60, v61
	v_cvt_pk_bf16_f32 v68, v70, v71
	v_cvt_pk_bf16_f32 v69, v66, v67
	v_cvt_pk_bf16_f32 v70, v64, v65
	v_cvt_pk_bf16_f32 v71, v0, v1
	ds_write_b128 v111, v[78:81] offset:34816
	ds_write_b128 v111, v[68:71] offset:34832
	s_and_saveexec_b64 s[90:91], s[48:49]
	v_exp_f32_e32 v0, v208
	ds_write_b32 v96, v0
	s_or_b64 exec, exec, s[90:91]
	s_cmpk_eq_i32 s63, 0x7c0
	s_waitcnt lgkmcnt(0)
	s_barrier
	s_cbranch_scc1 .LBB0_193
	v_add_u32_e32 v0, s63, v103
	v_cndmask_b32_e32 v0, v104, v0, vcc
	v_add_u32_e32 v0, s62, v0
	v_mad_i64_i32 v[0:1], s[14:15], v0, s8, v[84:85]
	v_lshl_add_u64 v[8:9], v[0:1], 0, s[58:59]
	v_lshl_add_u64 v[16:17], v[8:9], 0, s[88:89]
	global_load_dwordx4 v[8:11], v[0:1], off
	global_load_dwordx4 v[12:15], v[0:1], off offset:3072
	v_add_u32_e32 v0, s63, v101
	v_cndmask_b32_e32 v0, v102, v0, vcc
	v_add_u32_e32 v0, s62, v0
	v_mad_i64_i32 v[0:1], s[14:15], v0, s8, v[84:85]
	v_lshl_add_u64 v[24:25], v[0:1], 0, s[58:59]
	v_lshl_add_u64 v[24:25], v[24:25], 0, s[88:89]
	global_load_dwordx4 v[16:19], v[16:17], off offset:1024
	s_nop 0
	global_load_dwordx4 v[20:23], v[0:1], off
	s_nop 0
	global_load_dwordx4 v[24:27], v[24:25], off offset:1024
	s_nop 0
	global_load_dwordx4 v[28:31], v[0:1], off offset:3072
	s_branch .LBB0_193
